# out-projection sample units (run at the start of the FFN-up phase): consume step and drain rewritten with batched LDS reads, like the other sample-unit instances
# speedup vs baseline: 1.0023x; 1.0023x over previous
; #define MR_ISSUE(c) do { const unsigned sb_ = ldw + (unsigned)(((c) & (NS - 1)) * SLOT); glds16_m(src[0] + (size_t)(c) * 128, sb_); glds16_m(src[1] + (size_t)(c) * 128, sb_ + 8192u); } while (0)
; template <class Epi>
; __device__ __forceinline__ void mini_ring(PG8_LAS unsigned char* lds, const bf16_t* A, const bf16_t* Bt, int K, const Epi& E, int mu, int wave_u) {
;     ...
;     const int nmain = nchunk - PD;
; #pragma unroll 1
;     for (int c = 0; c < nmain; ++c) {
;         MR_ISSUE(c + PD);
;         asm volatile("s_waitcnt vmcnt(12)" ::: "memory"); __builtin_amdgcn_s_barrier(); asm volatile("" ::: "memory");
;         MR_CONSUME(c);
;     }
;     asm volatile("s_waitcnt vmcnt(10)" ::: "memory"); __builtin_amdgcn_s_barrier(); asm volatile("" ::: "memory"); MR_CONSUME(nmain);
;     asm volatile("s_waitcnt vmcnt(8)" ::: "memory"); __builtin_amdgcn_s_barrier(); asm volatile("" ::: "memory"); MR_CONSUME(nmain + 1);
;     asm volatile("s_waitcnt vmcnt(6)" ::: "memory"); __builtin_amdgcn_s_barrier(); asm volatile("" ::: "memory"); MR_CONSUME(nmain + 2);
.LBB0_1083:
	s_add_i32 s10, s1, 0x18000
	s_and_b32 s10, s10, 0x1c000
	s_add_i32 s10, s10, s0
	s_mov_b32 s11, m0
	s_mov_b32 m0, s10
	s_nop 0
	global_load_lds_dwordx4 v[6:7], off
	s_mov_b32 m0, s11
	s_addk_i32 s10, 0x2000
	s_mov_b32 s11, m0
	s_mov_b32 m0, s10
	s_nop 0
	global_load_lds_dwordx4 v[4:5], off
	s_mov_b32 m0, s11
	s_waitcnt vmcnt(12)
	s_barrier
	v_cndmask_b32_e64 v0, 0, 1, s[12:13]
	v_cmp_ne_u32_e64 s[10:11], 1, v0
	s_andn2_b64 vcc, exec, s[12:13]
	s_cbranch_vccnz .LBB0_1082
	s_and_b32 s17, s1, 0x1c000
	v_add_u32_e32 v0, s17, v12
	v_add_u32_e32 v2, v0, v10
	v_add_u32_e32 v3, s17, v11
	v_add_u32_e32 v13, v3, v10
	v_add_u32_e32 v0, v0, v9
	v_add_u32_e32 v3, v3, v9
	ds_read_b128 v[44:47], v13
	ds_read_b128 v[48:51], v2 offset:8192
	ds_read_b128 v[52:55], v2 offset:10240
	ds_read_b128 v[56:59], v2 offset:12288
	ds_read_b128 v[60:63], v2 offset:14336
	ds_read_b128 v[64:67], v3
	ds_read_b128 v[68:71], v0 offset:8192
	ds_read_b128 v[72:75], v0 offset:10240
	ds_read_b128 v[76:79], v0 offset:12288
	ds_read_b128 v[80:83], v0 offset:14336
	s_waitcnt lgkmcnt(8)
	v_mfma_f32_16x16x32_bf16 v[30:33], v[48:51], v[44:47], v[30:33]
	s_waitcnt lgkmcnt(7)
	v_mfma_f32_16x16x32_bf16 v[34:37], v[52:55], v[44:47], v[34:37]
	s_waitcnt lgkmcnt(6)
	v_mfma_f32_16x16x32_bf16 v[18:21], v[56:59], v[44:47], v[18:21]
	s_waitcnt lgkmcnt(5)
	v_mfma_f32_16x16x32_bf16 v[22:25], v[60:63], v[44:47], v[22:25]
	s_waitcnt lgkmcnt(3)
	v_mfma_f32_16x16x32_bf16 v[30:33], v[68:71], v[64:67], v[30:33]
	s_waitcnt lgkmcnt(2)
	v_mfma_f32_16x16x32_bf16 v[34:37], v[72:75], v[64:67], v[34:37]
	s_waitcnt lgkmcnt(1)
	v_mfma_f32_16x16x32_bf16 v[18:21], v[76:79], v[64:67], v[18:21]
	s_waitcnt lgkmcnt(0)
	v_mfma_f32_16x16x32_bf16 v[22:25], v[80:83], v[64:67], v[22:25]
	s_branch .LBB0_1082
.LBB0_1085:
	s_waitcnt vmcnt(10)
	s_barrier
	v_add_u32_e32 v0, 0, v11
	v_add_u32_e32 v5, 0, v12
	s_and_b64 vcc, exec, s[12:13]
	v_add_u32_e32 v4, v0, v10
	v_add_u32_e32 v3, v0, v9
	v_add_u32_e32 v2, v5, v10
	v_add_u32_e32 v0, v5, v9
	s_cbranch_vccz .LBB0_1087
	ds_read_b128 v[44:47], v4 offset:32768
	ds_read_b128 v[48:51], v2 offset:40960
	ds_read_b128 v[52:55], v2 offset:43008
	ds_read_b128 v[56:59], v2 offset:45056
	ds_read_b128 v[60:63], v2 offset:47104
	ds_read_b128 v[64:67], v3 offset:32768
	ds_read_b128 v[68:71], v0 offset:40960
	ds_read_b128 v[72:75], v0 offset:43008
	ds_read_b128 v[76:79], v0 offset:45056
	ds_read_b128 v[80:83], v0 offset:47104
	s_waitcnt lgkmcnt(8)
	v_mfma_f32_16x16x32_bf16 v[30:33], v[48:51], v[44:47], v[30:33]
	s_waitcnt lgkmcnt(7)
	v_mfma_f32_16x16x32_bf16 v[34:37], v[52:55], v[44:47], v[34:37]
	s_waitcnt lgkmcnt(6)
	v_mfma_f32_16x16x32_bf16 v[18:21], v[56:59], v[44:47], v[18:21]
	s_waitcnt lgkmcnt(5)
	v_mfma_f32_16x16x32_bf16 v[22:25], v[60:63], v[44:47], v[22:25]
	s_waitcnt lgkmcnt(3)
	v_mfma_f32_16x16x32_bf16 v[30:33], v[68:71], v[64:67], v[30:33]
	s_waitcnt lgkmcnt(2)
	v_mfma_f32_16x16x32_bf16 v[34:37], v[72:75], v[64:67], v[34:37]
	s_waitcnt lgkmcnt(1)
	v_mfma_f32_16x16x32_bf16 v[18:21], v[76:79], v[64:67], v[18:21]
	s_waitcnt lgkmcnt(0)
	v_mfma_f32_16x16x32_bf16 v[22:25], v[80:83], v[64:67], v[22:25]
.LBB0_1087:
	s_waitcnt vmcnt(8)
	s_barrier
	s_and_b64 vcc, exec, s[10:11]
	s_cbranch_vccnz .LBB0_1089
	ds_read_b128 v[44:47], v4 offset:49152
	ds_read_b128 v[48:51], v2 offset:57344
	ds_read_b128 v[52:55], v2 offset:59392
	ds_read_b128 v[56:59], v2 offset:61440
	ds_read_b128 v[60:63], v2 offset:63488
	ds_read_b128 v[64:67], v3 offset:49152
	ds_read_b128 v[68:71], v0 offset:57344
	ds_read_b128 v[72:75], v0 offset:59392
	ds_read_b128 v[76:79], v0 offset:61440
	ds_read_b128 v[80:83], v0 offset:63488
	s_waitcnt lgkmcnt(8)
	v_mfma_f32_16x16x32_bf16 v[30:33], v[48:51], v[44:47], v[30:33]
	s_waitcnt lgkmcnt(7)
	v_mfma_f32_16x16x32_bf16 v[34:37], v[52:55], v[44:47], v[34:37]
	s_waitcnt lgkmcnt(6)
	v_mfma_f32_16x16x32_bf16 v[18:21], v[56:59], v[44:47], v[18:21]
	s_waitcnt lgkmcnt(5)
	v_mfma_f32_16x16x32_bf16 v[22:25], v[60:63], v[44:47], v[22:25]
	s_waitcnt lgkmcnt(3)
	v_mfma_f32_16x16x32_bf16 v[30:33], v[68:71], v[64:67], v[30:33]
	s_waitcnt lgkmcnt(2)
	v_mfma_f32_16x16x32_bf16 v[34:37], v[72:75], v[64:67], v[34:37]
	s_waitcnt lgkmcnt(1)
	v_mfma_f32_16x16x32_bf16 v[18:21], v[76:79], v[64:67], v[18:21]
	s_waitcnt lgkmcnt(0)
	v_mfma_f32_16x16x32_bf16 v[22:25], v[80:83], v[64:67], v[22:25]
; template <class Epi>
; __device__ __forceinline__ void mini_ring(PG8_LAS unsigned char* lds, const bf16_t* A, const bf16_t* Bt, int K, const Epi& E, int mu, int wave_u) {
;     ...
;     asm volatile("s_waitcnt vmcnt(6)" ::: "memory"); __builtin_amdgcn_s_barrier(); asm volatile("" ::: "memory"); MR_CONSUME(nmain + 2);
;     asm volatile("s_waitcnt vmcnt(4)" ::: "memory"); __builtin_amdgcn_s_barrier(); asm volatile("" ::: "memory"); MR_CONSUME(nmain + 3);
;     asm volatile("s_waitcnt vmcnt(2)" ::: "memory"); __builtin_amdgcn_s_barrier(); asm volatile("" ::: "memory"); MR_CONSUME(nmain + 4);
;     asm volatile("s_waitcnt vmcnt(0)" ::: "memory"); __builtin_amdgcn_s_barrier(); asm volatile("" ::: "memory"); MR_CONSUME(nmain + 5);
.LBB0_1089:
	s_waitcnt vmcnt(6)
	s_barrier
	s_and_b64 vcc, exec, s[10:11]
	s_cbranch_vccnz .LBB0_1091
	s_mov_b32 s0, 0x10000
	v_add_u32_e32 v0, s0, v12
	v_add_u32_e32 v6, v0, v10
	v_add_u32_e32 v7, s0, v11
	v_add_u32_e32 v13, v7, v10
	v_add_u32_e32 v0, v0, v9
	v_add_u32_e32 v7, v7, v9
	ds_read_b128 v[44:47], v13
	ds_read_b128 v[48:51], v6 offset:8192
	ds_read_b128 v[52:55], v6 offset:10240
	ds_read_b128 v[56:59], v6 offset:12288
	ds_read_b128 v[60:63], v6 offset:14336
	ds_read_b128 v[64:67], v7
	ds_read_b128 v[68:71], v0 offset:8192
	ds_read_b128 v[72:75], v0 offset:10240
	ds_read_b128 v[76:79], v0 offset:12288
	ds_read_b128 v[80:83], v0 offset:14336
	s_waitcnt lgkmcnt(8)
	v_mfma_f32_16x16x32_bf16 v[30:33], v[48:51], v[44:47], v[30:33]
	s_waitcnt lgkmcnt(7)
	v_mfma_f32_16x16x32_bf16 v[34:37], v[52:55], v[44:47], v[34:37]
	s_waitcnt lgkmcnt(6)
	v_mfma_f32_16x16x32_bf16 v[18:21], v[56:59], v[44:47], v[18:21]
	s_waitcnt lgkmcnt(5)
	v_mfma_f32_16x16x32_bf16 v[22:25], v[60:63], v[44:47], v[22:25]
	s_waitcnt lgkmcnt(3)
	v_mfma_f32_16x16x32_bf16 v[30:33], v[68:71], v[64:67], v[30:33]
	s_waitcnt lgkmcnt(2)
	v_mfma_f32_16x16x32_bf16 v[34:37], v[72:75], v[64:67], v[34:37]
	s_waitcnt lgkmcnt(1)
	v_mfma_f32_16x16x32_bf16 v[18:21], v[76:79], v[64:67], v[18:21]
	s_waitcnt lgkmcnt(0)
	v_mfma_f32_16x16x32_bf16 v[22:25], v[80:83], v[64:67], v[22:25]
.LBB0_1091:
	s_waitcnt vmcnt(4)
	s_barrier
	s_and_b64 vcc, exec, s[10:11]
	s_cbranch_vccnz .LBB0_1093
	s_mov_b32 s0, 0x14000
	v_add_u32_e32 v0, s0, v12
	v_add_u32_e32 v6, v0, v10
	v_add_u32_e32 v7, s0, v11
	v_add_u32_e32 v13, v7, v10
	v_add_u32_e32 v0, v0, v9
	v_add_u32_e32 v7, v7, v9
	ds_read_b128 v[44:47], v13
	ds_read_b128 v[48:51], v6 offset:8192
	ds_read_b128 v[52:55], v6 offset:10240
	ds_read_b128 v[56:59], v6 offset:12288
	ds_read_b128 v[60:63], v6 offset:14336
	ds_read_b128 v[64:67], v7
	ds_read_b128 v[68:71], v0 offset:8192
	ds_read_b128 v[72:75], v0 offset:10240
	ds_read_b128 v[76:79], v0 offset:12288
	ds_read_b128 v[80:83], v0 offset:14336
	s_waitcnt lgkmcnt(8)
	v_mfma_f32_16x16x32_bf16 v[30:33], v[48:51], v[44:47], v[30:33]
	s_waitcnt lgkmcnt(7)
	v_mfma_f32_16x16x32_bf16 v[34:37], v[52:55], v[44:47], v[34:37]
	s_waitcnt lgkmcnt(6)
	v_mfma_f32_16x16x32_bf16 v[18:21], v[56:59], v[44:47], v[18:21]
	s_waitcnt lgkmcnt(5)
	v_mfma_f32_16x16x32_bf16 v[22:25], v[60:63], v[44:47], v[22:25]
	s_waitcnt lgkmcnt(3)
	v_mfma_f32_16x16x32_bf16 v[30:33], v[68:71], v[64:67], v[30:33]
	s_waitcnt lgkmcnt(2)
	v_mfma_f32_16x16x32_bf16 v[34:37], v[72:75], v[64:67], v[34:37]
	s_waitcnt lgkmcnt(1)
	v_mfma_f32_16x16x32_bf16 v[18:21], v[76:79], v[64:67], v[18:21]
	s_waitcnt lgkmcnt(0)
	v_mfma_f32_16x16x32_bf16 v[22:25], v[80:83], v[64:67], v[22:25]
.LBB0_1093:
	s_waitcnt vmcnt(2)
	s_barrier
	s_and_b64 vcc, exec, s[10:11]
	s_cbranch_vccnz .LBB0_1095
	s_mov_b32 s0, 0x18000
	v_add_u32_e32 v0, s0, v12
	v_add_u32_e32 v6, v0, v10
	v_add_u32_e32 v7, s0, v11
	v_add_u32_e32 v13, v7, v10
	v_add_u32_e32 v0, v0, v9
	v_add_u32_e32 v7, v7, v9
	ds_read_b128 v[44:47], v13
	ds_read_b128 v[48:51], v6 offset:8192
	ds_read_b128 v[52:55], v6 offset:10240
	ds_read_b128 v[56:59], v6 offset:12288
	ds_read_b128 v[60:63], v6 offset:14336
	ds_read_b128 v[64:67], v7
	ds_read_b128 v[68:71], v0 offset:8192
	ds_read_b128 v[72:75], v0 offset:10240
	ds_read_b128 v[76:79], v0 offset:12288
	ds_read_b128 v[80:83], v0 offset:14336
	s_waitcnt lgkmcnt(8)
	v_mfma_f32_16x16x32_bf16 v[30:33], v[48:51], v[44:47], v[30:33]
	s_waitcnt lgkmcnt(7)
	v_mfma_f32_16x16x32_bf16 v[34:37], v[52:55], v[44:47], v[34:37]
	s_waitcnt lgkmcnt(6)
	v_mfma_f32_16x16x32_bf16 v[18:21], v[56:59], v[44:47], v[18:21]
	s_waitcnt lgkmcnt(5)
	v_mfma_f32_16x16x32_bf16 v[22:25], v[60:63], v[44:47], v[22:25]
	s_waitcnt lgkmcnt(3)
	v_mfma_f32_16x16x32_bf16 v[30:33], v[68:71], v[64:67], v[30:33]
	s_waitcnt lgkmcnt(2)
	v_mfma_f32_16x16x32_bf16 v[34:37], v[72:75], v[64:67], v[34:37]
	s_waitcnt lgkmcnt(1)
	v_mfma_f32_16x16x32_bf16 v[18:21], v[76:79], v[64:67], v[18:21]
	s_waitcnt lgkmcnt(0)
	v_mfma_f32_16x16x32_bf16 v[22:25], v[80:83], v[64:67], v[22:25]
.LBB0_1095:
	s_waitcnt vmcnt(0)
	s_barrier
	s_and_b64 vcc, exec, s[10:11]
	s_cbranch_vccnz .LBB0_1097
	s_mov_b32 s0, 0x1c000
	v_add_u32_e32 v0, s0, v12
	v_add_u32_e32 v6, v0, v10
	v_add_u32_e32 v7, s0, v11
	v_add_u32_e32 v13, v7, v10
	v_add_u32_e32 v0, v0, v9
	v_add_u32_e32 v7, v7, v9
	ds_read_b128 v[44:47], v13
	ds_read_b128 v[48:51], v6 offset:8192
	ds_read_b128 v[52:55], v6 offset:10240
	ds_read_b128 v[56:59], v6 offset:12288
	ds_read_b128 v[60:63], v6 offset:14336
	ds_read_b128 v[64:67], v7
	ds_read_b128 v[68:71], v0 offset:8192
	ds_read_b128 v[72:75], v0 offset:10240
	ds_read_b128 v[76:79], v0 offset:12288
	ds_read_b128 v[80:83], v0 offset:14336
	s_waitcnt lgkmcnt(8)
	v_mfma_f32_16x16x32_bf16 v[30:33], v[48:51], v[44:47], v[30:33]
	s_waitcnt lgkmcnt(7)
	v_mfma_f32_16x16x32_bf16 v[34:37], v[52:55], v[44:47], v[34:37]
	s_waitcnt lgkmcnt(6)
	v_mfma_f32_16x16x32_bf16 v[18:21], v[56:59], v[44:47], v[18:21]
	s_waitcnt lgkmcnt(5)
	v_mfma_f32_16x16x32_bf16 v[22:25], v[60:63], v[44:47], v[22:25]
	s_waitcnt lgkmcnt(3)
	v_mfma_f32_16x16x32_bf16 v[30:33], v[68:71], v[64:67], v[30:33]
	s_waitcnt lgkmcnt(2)
	v_mfma_f32_16x16x32_bf16 v[34:37], v[72:75], v[64:67], v[34:37]
	s_waitcnt lgkmcnt(1)
	v_mfma_f32_16x16x32_bf16 v[18:21], v[76:79], v[64:67], v[18:21]
	s_waitcnt lgkmcnt(0)
	v_mfma_f32_16x16x32_bf16 v[22:25], v[80:83], v[64:67], v[22:25]
